# gating: each of a token's four lanes loads one quarter of the LayerNorm partial sums and two DPP quad steps combine them (was four redundant 64-byte loads)
# speedup vs baseline: 1.0128x; 1.0021x over previous
; __device__ __forceinline__ void gate_phase(int bx, int G, bool skip_ctx, const bf16* __restrict__ VG, const bf16* __restrict__ U, const float* __restrict__ stats, ...
;     ...
;     if (u < NU) GATE_LOAD(u);
.LBB0_39:
	s_cmpk_gt_i32 s3, 0x87f
	s_cbranch_scc1 .LBB0_51
	s_lshl_b32 s22, s12, 9
	s_ashr_i32 s23, s22, 31
	s_lshl_b64 s[26:27], s[22:23], 2
	s_waitcnt lgkmcnt(0)
	s_add_u32 s22, s8, s26
	s_addc_u32 s23, s9, s27
	s_add_u32 s26, s10, s26
	s_addc_u32 s27, s11, s27
	s_ashr_i32 s13, s12, 31
	s_lshl_b64 s[8:9], s[12:13], 18
	s_add_u32 s8, s28, s8
	s_addc_u32 s9, s29, s9
	s_add_u32 s38, s8, 0x5800000
	s_addc_u32 s39, s9, 0
	s_lshl_b32 s8, s12, 10
	s_ashr_i32 s9, s8, 31
	s_lshl_b64 s[8:9], s[8:9], 2
	s_add_u32 s6, s6, s8
	s_addc_u32 s7, s7, s9
	v_ashrrev_i32_e32 v100, 2, v4
	s_movk_i32 s8, 0xffe0
	v_bfi_b32 v102, s8, v100, v4
	s_add_u32 s8, s28, 0x11efa000
	s_addc_u32 s9, s29, 0
	s_add_u32 s10, s28, 0x140fa000
	s_addc_u32 s11, s29, 0
	s_ashr_i32 s46, s3, 3
	s_ashr_i32 s47, s46, 31
	v_lshlrev_b32_e32 v0, 4, v4
	s_lshl_b64 s[46:47], s[46:47], 7
	v_ashrrev_i32_e32 v101, 31, v100
	v_and_b32_e32 v6, 48, v0
	v_lshl_add_u64 v[0:1], s[46:47], 0, v[100:101]
	s_and_b32 s13, s3, 7
	v_lshlrev_b64 v[2:3], 6, v[0:1]
	v_lshlrev_b64 v[0:1], 10, v[0:1]
	v_lshl_add_u64 v[0:1], s[10:11], 0, v[0:1]
	s_lshl_b32 s72, s13, 7
	v_lshl_add_u64 v[0:1], v[0:1], 0, s[72:73]
	v_lshlrev_b32_e32 v160, 1, v6
	v_lshl_add_u64 v[2:3], s[40:41], 0, v[2:3]
	v_lshl_add_u64 v[0:1], v[0:1], 0, v[160:161]
	v_ashrrev_i32_e32 v103, 31, v102
	v_mov_b32_e32 v180, v6
	v_mov_b32_e32 v181, v161
	v_lshl_add_u64 v[2:3], v[2:3], 0, v[180:181]
	global_load_dwordx4 v[28:31], v[2:3], off
	global_load_dwordx4 v[32:35], v[0:1], off offset:16 nt
	global_load_dwordx4 v[36:39], v[0:1], off nt
	v_lshl_add_u64 v[0:1], s[46:47], 0, v[102:103]
	v_lshlrev_b64 v[0:1], 10, v[0:1]
	v_lshrrev_b32_e32 v2, 1, v4
	v_lshl_add_u64 v[0:1], s[8:9], 0, v[0:1]
	v_and_b32_e32 v8, 32, v2
	v_bfe_u32 v5, v4, 5, 1
	v_lshl_add_u64 v[0:1], v[0:1], 0, s[72:73]
	v_lshlrev_b32_e32 v160, 1, v8
	v_lshl_add_u64 v[0:1], v[0:1], 0, v[160:161]
	v_lshlrev_b32_e32 v160, 5, v5
	v_lshl_add_u64 v[0:1], v[0:1], 0, v[160:161]
	global_load_dwordx4 v[126:129], v[0:1], off nt
	global_load_dwordx4 v[130:133], v[0:1], off offset:16 nt
	v_lshl_add_u64 v[0:1], s[72:73], 0, v[102:103]
	v_lshlrev_b64 v[0:1], 8, v[0:1]
	v_lshl_add_u64 v[0:1], s[38:39], 0, v[0:1]
	v_lshlrev_b32_e32 v160, 4, v5
	v_lshl_add_u64 v[10:11], v[0:1], 0, v[160:161]
	global_load_dwordx4 v[0:3], v[10:11], off
	global_load_dwordx4 v[60:63], v[10:11], off offset:32
	global_load_dwordx4 v[64:67], v[10:11], off offset:64
	global_load_dwordx4 v[52:55], v[10:11], off offset:96
	global_load_dwordx4 v[56:59], v[10:11], off offset:128
	global_load_dwordx4 v[48:51], v[10:11], off offset:160
	global_load_dwordx4 v[44:47], v[10:11], off offset:192
	global_load_dwordx4 v[40:43], v[10:11], off offset:224
	v_lshlrev_b32_e32 v10, 4, v5
	v_lshlrev_b32_e32 v12, 2, v6
	v_mov_b32_e32 v13, v161
	v_and_or_b32 v4, v4, 31, v8
	s_movk_i32 s13, 0x110
	v_mul_u32_u24_e32 v9, 0x88, v6
	v_lshl_add_u64 v[104:105], s[22:23], 0, v[12:13]
	v_lshl_add_u64 v[108:109], s[26:27], 0, v[12:13]
	v_lshlrev_b32_e32 v5, 1, v100
	v_mad_u32_u24 v7, v4, s13, 0
	v_or_b32_e32 v4, v10, v8
	v_lshlrev_b64 v[12:13], 11, v[102:103]
	v_lshlrev_b32_e32 v9, 1, v9
	v_lshl_add_u64 v[110:111], s[38:39], 0, v[160:161]
	v_lshl_add_u64 v[112:113], s[16:17], 0, v[12:13]
	v_add3_u32 v134, 0, v5, v9
	v_add3_u32 v135, 0, v9, v5
	v_lshlrev_b32_e32 v114, 1, v6
	v_lshlrev_b32_e32 v116, 1, v8
	v_lshlrev_b32_e32 v118, 1, v10
	v_add_u32_e32 v136, v7, v160
	v_lshlrev_b32_e32 v160, 1, v4
	s_and_b32 s37, s3, 7
	s_lshl_b32 s38, s37, 8
	s_mov_b32 s39, 0
	v_lshl_add_u64 v[252:253], v[104:105], 0, s[38:39]
	global_load_dwordx4 v[218:221], v[252:253], off
	global_load_dwordx4 v[222:225], v[252:253], off offset:16
	global_load_dwordx4 v[226:229], v[252:253], off offset:32
	global_load_dwordx4 v[230:233], v[252:253], off offset:48
	v_lshl_add_u64 v[252:253], v[108:109], 0, s[38:39]
	global_load_dwordx4 v[234:237], v[252:253], off
	global_load_dwordx4 v[238:241], v[252:253], off offset:16
	global_load_dwordx4 v[242:245], v[252:253], off offset:32
	global_load_dwordx4 v[246:249], v[252:253], off offset:48
	v_lshl_add_u32 v252, s37, 7, v102
	v_ashrrev_i32_e32 v253, 31, v252
	v_lshl_add_u64 v[252:253], v[252:253], 2, s[6:7]
	global_load_dword v137, v[252:253], off
	s_waitcnt vmcnt(0)
	v_permlane32_swap_b32_e32 v126, v128
	v_permlane32_swap_b32_e32 v127, v129
	v_permlane32_swap_b32_e32 v130, v132
	v_permlane32_swap_b32_e32 v131, v133
	v_mov_b64_e32 v[124:125], v[126:127]
	v_mov_b64_e32 v[122:123], v[130:131]
	v_mov_b64_e32 v[120:121], v[128:129]
	v_mov_b64_e32 v[106:107], v[132:133]
	s_branch .LBB0_45

; __device__ __forceinline__ unsigned f2bf(float f) { unsigned u = __builtin_bit_cast(unsigned, f); return (u + 0x7fffu + ((u >> 16) & 1u)) >> 16; }
; __device__ __forceinline__ float bflo(unsigned w) { return __uint_as_float(w << 16); }
; __device__ __forceinline__ float bfhi(unsigned w) { return __uint_as_float(w & 0xffff0000u); }
; __device__ __forceinline__ void gate_phase(int bx, int G, bool skip_ctx, const bf16* __restrict__ VG, const bf16* __restrict__ U, const float* __restrict__ stats, ...
;     ...
;         const int chunk = u >> 3, h = u & 7;
;         {
;             const float s1 = (R.sa[0] + R.sa[2]) + (R.sb[0] + R.sb[2]) + (R.sc[0] + R.sc[2]) + (R.sd[0] + R.sd[2]);
;             const float s2 = (R.sa[1] + R.sa[3]) + (R.sb[1] + R.sb[3]) + (R.sc[1] + R.sc[3]) + (R.sd[1] + R.sd[3]);
;             const float mean = s1 * (1.0f / 512.0f);
;             const float var = fmaxf(s2 * (1.0f / 512.0f) - mean * mean, 0.f);
;             const float rstd = __builtin_amdgcn_rsqf(var + EPS);
;             const float* gp = gsg + h * 64 + dc; const float* bp = bsg + h * 64 + dc;
; #pragma unroll
;             for (int i = 0; i < 8; ++i) {
;                 const unsigned w = i < 4 ? R.v0[i] : R.v1[i - 4];
;                 const float x0 = (bflo(w) - mean) * rstd * gp[2 * i] + bp[2 * i], x1 = (bfhi(w) - mean) * rstd * gp[2 * i + 1] + bp[2 * i + 1];
;                 T[(dc + 2 * i) * GT_PITCH + q] = (bf16)f2bf(x0); T[(dc + 2 * i + 1) * GT_PITCH + q] = (bf16)f2bf(x1);
;             }
.LBB0_45:
	s_and_b32 s22, s3, 7
	s_lshl_b32 s72, s22, 8
	s_waitcnt vmcnt(23)
	v_add_f32_e32 v90, v28, v30
	v_add_f32_e32 v91, v29, v31
	s_nop 1
	v_add_f32_dpp v90, v90, v90 quad_perm:[1,0,3,2] row_mask:0xf bank_mask:0xf
	v_add_f32_dpp v91, v91, v91 quad_perm:[1,0,3,2] row_mask:0xf bank_mask:0xf
	s_nop 1
	v_add_f32_dpp v90, v90, v90 quad_perm:[2,3,0,1] row_mask:0xf bank_mask:0xf
	v_add_f32_dpp v91, v91, v91 quad_perm:[2,3,0,1] row_mask:0xf bank_mask:0xf
	s_nop 0
	s_nop 0
	v_mul_f32_e32 v115, 0x3b000000, v90
	s_lshl_b32 s19, s22, 6
	v_mul_f32_e32 v115, v115, v115
	s_mov_b32 s22, 0x3b000000
	v_fma_f32 v91, v91, s22, -v115
	v_max_f32_e32 v91, 0, v91
	v_add_f32_e32 v91, 0x358637bd, v91
	v_rsq_f32_e32 v91, v91
	s_waitcnt vmcnt(21)
	v_lshlrev_b32_e32 v92, 16, v36
	v_lshlrev_b32_e32 v94, 16, v37
	v_lshlrev_b32_e32 v96, 16, v38
	v_and_b32_e32 v93, 0xffff0000, v36
	v_and_b32_e32 v95, 0xffff0000, v37
	v_and_b32_e32 v97, 0xffff0000, v38
	v_fmac_f32_e32 v92, 0xbb000000, v90
	v_fmac_f32_e32 v94, 0xbb000000, v90
	v_fmac_f32_e32 v96, 0xbb000000, v90
	v_lshlrev_b32_e32 v98, 16, v39
	v_fmac_f32_e32 v93, 0xbb000000, v90
	v_fmac_f32_e32 v95, 0xbb000000, v90
	v_fmac_f32_e32 v97, 0xbb000000, v90
	v_mul_f32_e32 v88, v92, v91
	v_mul_f32_e32 v92, v94, v91
	v_mul_f32_e32 v94, v96, v91
	v_fmac_f32_e32 v98, 0xbb000000, v90
	v_mul_f32_e32 v89, v93, v91
	v_mul_f32_e32 v93, v95, v91
	v_mul_f32_e32 v95, v97, v91
	v_and_b32_e32 v99, 0xffff0000, v39
	v_mul_f32_e32 v96, v98, v91
	v_fmac_f32_e32 v99, 0xbb000000, v90
	v_mul_f32_e32 v97, v99, v91
	s_mov_b32 s13, s3
	s_waitcnt vmcnt(0)
	v_fma_f32 v68, v88, v218, v234
	v_fma_f32 v69, v89, v219, v235
	v_fma_f32 v12, v94, v222, v238
	v_fma_f32 v70, v92, v220, v236
	v_fma_f32 v71, v93, v221, v237
	v_fma_f32 v13, v95, v223, v239
	v_bfe_u32 v72, v68, 16, 1
	v_bfe_u32 v76, v12, 16, 1
	v_fma_f32 v14, v96, v224, v240
	v_bfe_u32 v73, v69, 16, 1
	v_bfe_u32 v74, v70, 16, 1
	v_bfe_u32 v75, v71, 16, 1
	v_bfe_u32 v77, v13, 16, 1
	v_add3_u32 v68, v68, v72, s56
	v_add3_u32 v12, v12, v76, s56
	v_add3_u32 v69, v69, v73, s56
	v_add3_u32 v70, v70, v74, s56
	v_add3_u32 v71, v71, v75, s56
	v_add3_u32 v13, v13, v77, s56
	ds_write_b16_d16_hi v134, v68
	ds_write_b16_d16_hi v135, v69 offset:272
	ds_write_b16_d16_hi v134, v70 offset:544
	ds_write_b16_d16_hi v135, v71 offset:816
	ds_write_b16_d16_hi v134, v12 offset:1088
	ds_write_b16_d16_hi v135, v13 offset:1360
	v_bfe_u32 v12, v14, 16, 1
	v_fma_f32 v15, v97, v225, v241
	v_add3_u32 v12, v14, v12, s56
	ds_write_b16_d16_hi v134, v12 offset:1632
	v_bfe_u32 v12, v15, 16, 1
	v_add3_u32 v12, v15, v12, s56
	ds_write_b16_d16_hi v135, v12 offset:1904
	v_lshlrev_b32_e32 v12, 16, v32
	v_fmac_f32_e32 v12, 0xbb000000, v90
	v_mul_f32_e32 v12, v12, v91
	v_fma_f32 v4, v12, v226, v242
	v_and_b32_e32 v8, 0xffff0000, v32
	v_fmac_f32_e32 v8, 0xbb000000, v90
	v_mul_f32_e32 v8, v8, v91
	v_fma_f32 v5, v8, v227, v243
	v_bfe_u32 v8, v4, 16, 1
	v_add3_u32 v4, v4, v8, s56
	ds_write_b16_d16_hi v134, v4 offset:2176
	v_bfe_u32 v4, v5, 16, 1
	v_add3_u32 v4, v5, v4, s56
	ds_write_b16_d16_hi v135, v4 offset:2448
	v_lshlrev_b32_e32 v4, 16, v33
	v_fmac_f32_e32 v4, 0xbb000000, v90
	v_and_b32_e32 v5, 0xffff0000, v33
	v_mul_f32_e32 v4, v4, v91
	v_fmac_f32_e32 v5, 0xbb000000, v90
	v_fma_f32 v4, v4, v228, v244
	v_mul_f32_e32 v5, v5, v91
	v_fma_f32 v7, v5, v229, v245
	v_bfe_u32 v5, v4, 16, 1
	v_add3_u32 v4, v4, v5, s56
	ds_write_b16_d16_hi v134, v4 offset:2720
	v_bfe_u32 v4, v7, 16, 1
	v_add3_u32 v4, v7, v4, s56
	ds_write_b16_d16_hi v135, v4 offset:2992
	v_lshlrev_b32_e32 v4, 16, v34
	v_fmac_f32_e32 v4, 0xbb000000, v90
	v_mul_f32_e32 v4, v4, v91
	v_and_b32_e32 v5, 0xffff0000, v34
	v_fma_f32 v4, v4, v230, v246
	v_fmac_f32_e32 v5, 0xbb000000, v90
	v_mul_f32_e32 v5, v5, v91
	v_bfe_u32 v6, v4, 16, 1
	v_fma_f32 v5, v5, v231, v247
	v_add3_u32 v4, v4, v6, s56
	ds_write_b16_d16_hi v134, v4 offset:3264
	v_bfe_u32 v4, v5, 16, 1
	v_add3_u32 v4, v5, v4, s56
	ds_write_b16_d16_hi v135, v4 offset:3536
	v_lshlrev_b32_e32 v4, 16, v35
	v_fmac_f32_e32 v4, 0xbb000000, v90
	v_and_b32_e32 v5, 0xffff0000, v35
	v_mul_f32_e32 v4, v4, v91
	v_fmac_f32_e32 v5, 0xbb000000, v90
	v_fma_f32 v4, v4, v232, v248
	v_mul_f32_e32 v5, v5, v91
	v_fma_f32 v87, v5, v233, v249
	v_bfe_u32 v5, v4, 16, 1
	v_add3_u32 v4, v4, v5, s56
	ds_write_b16_d16_hi v134, v4 offset:3808
	v_bfe_u32 v4, v87, 16, 1
	v_add3_u32 v4, v87, v4, s56
	ds_write_b16_d16_hi v135, v4 offset:4080
	s_branch .LBB0_47

; __device__ __forceinline__ void gate_phase(int bx, int G, bool skip_ctx, const bf16* __restrict__ VG, const bf16* __restrict__ U, const float* __restrict__ stats, ...
;     ...
;     if (u < NU) GATE_LOAD(u);
.LBB0_49:
	v_mov_b64_e32 v[70:71], v[2:3]
	v_mov_b64_e32 v[74:75], v[62:63]
	v_mov_b64_e32 v[78:79], v[66:67]
	v_mov_b64_e32 v[82:83], v[54:55]
	v_mov_b64_e32 v[86:87], v[58:59]
	v_mov_b64_e32 v[90:91], v[50:51]
	v_mov_b64_e32 v[94:95], v[46:47]
	v_mov_b64_e32 v[98:99], v[42:43]
	s_mov_b64 s[22:23], 0
	s_andn2_b64 vcc, exec, s[38:39]
	v_mov_b64_e32 v[126:127], v[124:125]
	v_mov_b64_e32 v[128:129], v[122:123]
	v_mov_b64_e32 v[130:131], v[120:121]
	v_mov_b64_e32 v[132:133], v[106:107]
	v_mov_b64_e32 v[68:69], v[0:1]
	v_mov_b64_e32 v[72:73], v[60:61]
	v_mov_b64_e32 v[76:77], v[64:65]
	v_mov_b64_e32 v[80:81], v[52:53]
	v_mov_b64_e32 v[84:85], v[56:57]
	v_mov_b64_e32 v[88:89], v[48:49]
	v_mov_b64_e32 v[92:93], v[44:45]
	v_mov_b64_e32 v[96:97], v[40:41]
	s_cbranch_vccz .LBB0_44
	s_ashr_i32 s27, s26, 31
	s_lshl_b64 s[22:23], s[26:27], 7
	v_lshl_add_u64 v[4:5], s[22:23], 0, v[100:101]
	s_and_b32 s25, s3, 7
	v_lshlrev_b64 v[6:7], 6, v[4:5]
	v_lshlrev_b64 v[4:5], 10, v[4:5]
	v_lshl_add_u64 v[4:5], s[10:11], 0, v[4:5]
	s_lshl_b32 s72, s25, 7
	v_lshl_add_u64 v[4:5], v[4:5], 0, s[72:73]
	v_mov_b32_e32 v115, v161
	v_lshl_add_u64 v[6:7], s[40:41], 0, v[6:7]
	v_lshl_add_u64 v[4:5], v[4:5], 0, v[114:115]
	v_lshrrev_b32_e32 v180, 1, v114
	v_mov_b32_e32 v181, v161
	v_lshl_add_u64 v[6:7], v[6:7], 0, v[180:181]
	global_load_dwordx4 v[28:31], v[6:7], off
	global_load_dwordx4 v[32:35], v[4:5], off offset:16 nt
	global_load_dwordx4 v[36:39], v[4:5], off nt
	v_lshl_add_u64 v[4:5], s[22:23], 0, v[102:103]
	v_lshlrev_b64 v[4:5], 10, v[4:5]
	v_lshl_add_u64 v[4:5], s[8:9], 0, v[4:5]
	v_lshl_add_u64 v[4:5], v[4:5], 0, s[72:73]
	v_mov_b32_e32 v117, v161
	v_lshl_add_u64 v[4:5], v[4:5], 0, v[116:117]
	v_mov_b32_e32 v119, v161
	v_lshl_add_u64 v[4:5], v[4:5], 0, v[118:119]
	global_load_dwordx4 v[126:129], v[4:5], off nt
	global_load_dwordx4 v[130:133], v[4:5], off offset:16 nt
	v_lshl_add_u64 v[4:5], s[72:73], 0, v[102:103]
	v_lshlrev_b64 v[4:5], 8, v[4:5]
	v_lshl_add_u64 v[4:5], v[110:111], 0, v[4:5]
	s_mov_b64 s[22:23], -1
	s_branch .LBB0_44
